# attention interleaved PV/softmax; waves 4-7 defer only the 8 second-half PV MFMAs
# speedup vs baseline: 1.0224x; 1.0109x over previous
.Lab_B:
	s_cmp_eq_u32 s42, 0
	s_cbranch_scc1 .Lab_B0
	v_mfma_f32_32x32x16_bf16 v[128:143], v[216:219], v[200:203], v[128:143]
	v_mfma_f32_32x32x16_bf16 v[96:111], v[224:227], v[200:203], v[96:111]
	v_mfma_f32_32x32x16_bf16 v[64:79], v[232:235], v[200:203], v[64:79]
	v_mfma_f32_32x32x16_bf16 v[32:47], v[244:247], v[200:203], v[32:47]
	v_mfma_f32_32x32x16_bf16 v[128:143], v[220:223], v[204:207], v[128:143]
	v_mfma_f32_32x32x16_bf16 v[96:111], v[228:231], v[204:207], v[96:111]
	v_mfma_f32_32x32x16_bf16 v[64:79], v[236:239], v[204:207], v[64:79]
	v_mfma_f32_32x32x16_bf16 v[32:47], v[248:251], v[204:207], v[32:47]
.Lab_B0:
	ds_read_b128 v[216:219], v199 offset:0
	ds_read_b128 v[232:235], v193 offset:0
	ds_read_b128 v[220:223], v199 offset:32
	ds_read_b128 v[236:239], v193 offset:32
	ds_read_b128 v[224:227], v199 offset:64
	ds_read_b128 v[244:247], v193 offset:64
	ds_read_b128 v[228:231], v199 offset:96
	ds_read_b128 v[248:251], v193 offset:96
	s_waitcnt lgkmcnt(6)
	v_mfma_f32_32x32x16_bf16 v[144:159], v[216:219], v[232:235], v[0:15]
	s_waitcnt lgkmcnt(4)
	v_mfma_f32_32x32x16_bf16 v[144:159], v[220:223], v[236:239], v[144:159]
	s_waitcnt lgkmcnt(2)
	v_mfma_f32_32x32x16_bf16 v[144:159], v[224:227], v[244:247], v[144:159]
	s_waitcnt lgkmcnt(0)
	v_mfma_f32_32x32x16_bf16 v[144:159], v[228:231], v[248:251], v[144:159]
	ds_read_b128 v[216:219], v199 offset:9216
	ds_read_b128 v[232:235], v193 offset:36864
	ds_read_b128 v[220:223], v199 offset:9248
	ds_read_b128 v[236:239], v193 offset:36896
	ds_read_b128 v[224:227], v199 offset:9280
	ds_read_b128 v[244:247], v193 offset:36928
	ds_read_b128 v[228:231], v199 offset:9312
	ds_read_b128 v[248:251], v193 offset:36960
	s_nop 3
	v_exp_f32_e32 v144, v144
	v_exp_f32_e32 v145, v145
	v_exp_f32_e32 v146, v146
	v_exp_f32_e32 v147, v147
	v_exp_f32_e32 v148, v148
	v_exp_f32_e32 v149, v149
	v_exp_f32_e32 v150, v150
	v_exp_f32_e32 v151, v151
	v_exp_f32_e32 v152, v152
	v_exp_f32_e32 v153, v153
	v_exp_f32_e32 v154, v154
	v_exp_f32_e32 v155, v155
	v_exp_f32_e32 v156, v156
	v_exp_f32_e32 v157, v157
	v_exp_f32_e32 v158, v158
	v_exp_f32_e32 v159, v159
	v_add_f32_e32 v243, v144, v145
	v_add_f32_e32 v243, v146, v243
	v_add_f32_e32 v243, v147, v243
	v_add_f32_e32 v243, v148, v243
	v_add_f32_e32 v243, v149, v243
	v_add_f32_e32 v243, v150, v243
	v_add_f32_e32 v243, v151, v243
	s_waitcnt lgkmcnt(6)
	v_mfma_f32_32x32x16_bf16 v[200:215], v[216:219], v[232:235], v[0:15]
	s_waitcnt lgkmcnt(4)
	v_mfma_f32_32x32x16_bf16 v[200:215], v[220:223], v[236:239], v[200:215]
	s_waitcnt lgkmcnt(2)
	v_mfma_f32_32x32x16_bf16 v[200:215], v[224:227], v[244:247], v[200:215]
	s_waitcnt lgkmcnt(0)
	v_mfma_f32_32x32x16_bf16 v[200:215], v[228:231], v[248:251], v[200:215]
	ds_read_b128 v[216:219], v198 offset:0
	ds_read_b128 v[224:227], v198 offset:4608
	ds_read_b128 v[232:235], v198 offset:9216
	ds_read_b128 v[244:247], v198 offset:13824
	ds_read_b128 v[220:223], v198 offset:32
	ds_read_b128 v[228:231], v198 offset:4640
	ds_read_b128 v[236:239], v198 offset:9248
	ds_read_b128 v[248:251], v198 offset:13856
	v_add_f32_e32 v243, v152, v243
	v_add_f32_e32 v243, v153, v243
	v_add_f32_e32 v243, v154, v243
	v_add_f32_e32 v243, v155, v243
	v_add_f32_e32 v243, v156, v243
	v_add_f32_e32 v243, v157, v243
	v_add_f32_e32 v243, v158, v243
	v_add_f32_e32 v243, v159, v243
	v_add_f32_e32 v196, v196, v243
	v_cvt_pk_bf16_f32 v144, v144, v145
	v_cvt_pk_bf16_f32 v145, v146, v147
	v_cvt_pk_bf16_f32 v146, v148, v149
	v_cvt_pk_bf16_f32 v147, v150, v151
	v_cvt_pk_bf16_f32 v148, v152, v153
	v_cvt_pk_bf16_f32 v149, v154, v155
	v_cvt_pk_bf16_f32 v150, v156, v157
	v_cvt_pk_bf16_f32 v151, v158, v159
	s_waitcnt lgkmcnt(7)
	v_mfma_f32_32x32x16_bf16 v[112:127], v[216:219], v[144:147], v[112:127]
	v_exp_f32_e32 v200, v200
	v_exp_f32_e32 v201, v201
	v_exp_f32_e32 v202, v202
	v_exp_f32_e32 v203, v203
	v_exp_f32_e32 v204, v204
	s_waitcnt lgkmcnt(6)
	v_mfma_f32_32x32x16_bf16 v[80:95], v[224:227], v[144:147], v[80:95]
	v_exp_f32_e32 v205, v205
	v_exp_f32_e32 v206, v206
	v_exp_f32_e32 v207, v207
	v_exp_f32_e32 v208, v208
	v_exp_f32_e32 v209, v209
	s_waitcnt lgkmcnt(5)
	v_mfma_f32_32x32x16_bf16 v[48:63], v[232:235], v[144:147], v[48:63]
	v_exp_f32_e32 v210, v210
	v_exp_f32_e32 v211, v211
	v_exp_f32_e32 v212, v212
	v_exp_f32_e32 v213, v213
	v_exp_f32_e32 v214, v214
	s_waitcnt lgkmcnt(4)
	v_mfma_f32_32x32x16_bf16 v[16:31], v[244:247], v[144:147], v[16:31]
	v_exp_f32_e32 v215, v215
	v_add_f32_e32 v243, v200, v201
	v_add_f32_e32 v243, v202, v243
	v_add_f32_e32 v243, v203, v243
	v_add_f32_e32 v243, v204, v243
	s_waitcnt lgkmcnt(3)
	v_mfma_f32_32x32x16_bf16 v[112:127], v[220:223], v[148:151], v[112:127]
	v_add_f32_e32 v243, v205, v243
	v_add_f32_e32 v243, v206, v243
	v_add_f32_e32 v243, v207, v243
	v_add_f32_e32 v243, v208, v243
	v_add_f32_e32 v243, v209, v243
	s_waitcnt lgkmcnt(2)
	v_mfma_f32_32x32x16_bf16 v[80:95], v[228:231], v[148:151], v[80:95]
	v_add_f32_e32 v243, v210, v243
	v_add_f32_e32 v243, v211, v243
	v_add_f32_e32 v243, v212, v243
	v_add_f32_e32 v243, v213, v243
	v_add_f32_e32 v243, v214, v243
	s_waitcnt lgkmcnt(1)
	v_mfma_f32_32x32x16_bf16 v[48:63], v[236:239], v[148:151], v[48:63]
	v_add_f32_e32 v243, v215, v243
	v_add_f32_e32 v197, v197, v243
	v_cvt_pk_bf16_f32 v200, v200, v201
	v_cvt_pk_bf16_f32 v201, v202, v203
	v_cvt_pk_bf16_f32 v202, v204, v205
	s_waitcnt lgkmcnt(0)
	v_mfma_f32_32x32x16_bf16 v[16:31], v[248:251], v[148:151], v[16:31]
	v_cvt_pk_bf16_f32 v203, v206, v207
	v_cvt_pk_bf16_f32 v204, v208, v209
	v_cvt_pk_bf16_f32 v205, v210, v211
	v_cvt_pk_bf16_f32 v206, v212, v213
	v_cvt_pk_bf16_f32 v207, v214, v215
	s_nop 1
	v_mfma_f32_32x32x16_bf16 v[128:143], v[216:219], v[200:203], v[128:143]
	v_mfma_f32_32x32x16_bf16 v[96:111], v[224:227], v[200:203], v[96:111]
	v_mfma_f32_32x32x16_bf16 v[64:79], v[232:235], v[200:203], v[64:79]
	v_mfma_f32_32x32x16_bf16 v[32:47], v[244:247], v[200:203], v[32:47]
	v_mfma_f32_32x32x16_bf16 v[128:143], v[220:223], v[204:207], v[128:143]
	v_mfma_f32_32x32x16_bf16 v[96:111], v[228:231], v[204:207], v[96:111]
	v_mfma_f32_32x32x16_bf16 v[64:79], v[236:239], v[204:207], v[64:79]
	v_mfma_f32_32x32x16_bf16 v[32:47], v[248:251], v[204:207], v[32:47]
	ds_read_b128 v[216:219], v199 offset:4608
	ds_read_b128 v[232:235], v193 offset:0
	ds_read_b128 v[220:223], v199 offset:4640
	ds_read_b128 v[236:239], v193 offset:32
	ds_read_b128 v[224:227], v199 offset:4672
	ds_read_b128 v[244:247], v193 offset:64
	ds_read_b128 v[228:231], v199 offset:4704
	ds_read_b128 v[248:251], v193 offset:96
	s_waitcnt lgkmcnt(6)
	v_mfma_f32_32x32x16_bf16 v[144:159], v[216:219], v[232:235], v[0:15]
	s_waitcnt lgkmcnt(4)
	v_mfma_f32_32x32x16_bf16 v[144:159], v[220:223], v[236:239], v[144:159]
	s_waitcnt lgkmcnt(2)
	v_mfma_f32_32x32x16_bf16 v[144:159], v[224:227], v[244:247], v[144:159]
	s_waitcnt lgkmcnt(0)
	v_mfma_f32_32x32x16_bf16 v[144:159], v[228:231], v[248:251], v[144:159]
	ds_read_b128 v[216:219], v199 offset:13824
	ds_read_b128 v[232:235], v193 offset:36864
	ds_read_b128 v[220:223], v199 offset:13856
	ds_read_b128 v[236:239], v193 offset:36896
	ds_read_b128 v[224:227], v199 offset:13888
	ds_read_b128 v[244:247], v193 offset:36928
	ds_read_b128 v[228:231], v199 offset:13920
	ds_read_b128 v[248:251], v193 offset:36960
	s_nop 3
	v_exp_f32_e32 v144, v144
	v_exp_f32_e32 v145, v145
	v_exp_f32_e32 v146, v146
	v_exp_f32_e32 v147, v147
	v_exp_f32_e32 v148, v148
	v_exp_f32_e32 v149, v149
	v_exp_f32_e32 v150, v150
	v_exp_f32_e32 v151, v151
	v_exp_f32_e32 v152, v152
	v_exp_f32_e32 v153, v153
	v_exp_f32_e32 v154, v154
	v_exp_f32_e32 v155, v155
	v_exp_f32_e32 v156, v156
	v_exp_f32_e32 v157, v157
	v_exp_f32_e32 v158, v158
	v_exp_f32_e32 v159, v159
	v_add_f32_e32 v243, v144, v145
	v_add_f32_e32 v243, v146, v243
	v_add_f32_e32 v243, v147, v243
	v_add_f32_e32 v243, v148, v243
	v_add_f32_e32 v243, v149, v243
	v_add_f32_e32 v243, v150, v243
	v_add_f32_e32 v243, v151, v243
	s_waitcnt lgkmcnt(6)
	v_mfma_f32_32x32x16_bf16 v[200:215], v[216:219], v[232:235], v[0:15]
	s_waitcnt lgkmcnt(4)
	v_mfma_f32_32x32x16_bf16 v[200:215], v[220:223], v[236:239], v[200:215]
	s_waitcnt lgkmcnt(2)
	v_mfma_f32_32x32x16_bf16 v[200:215], v[224:227], v[244:247], v[200:215]
	s_waitcnt lgkmcnt(0)
	v_mfma_f32_32x32x16_bf16 v[200:215], v[228:231], v[248:251], v[200:215]
	ds_read_b128 v[216:219], v198 offset:64
	ds_read_b128 v[224:227], v198 offset:4672
	ds_read_b128 v[232:235], v198 offset:9280
	ds_read_b128 v[244:247], v198 offset:13888
	ds_read_b128 v[220:223], v198 offset:96
	ds_read_b128 v[228:231], v198 offset:4704
	ds_read_b128 v[236:239], v198 offset:9312
	ds_read_b128 v[248:251], v198 offset:13920
	v_add_f32_e32 v243, v152, v243
	v_add_f32_e32 v243, v153, v243
	v_add_f32_e32 v243, v154, v243
	v_add_f32_e32 v243, v155, v243
	v_add_f32_e32 v243, v156, v243
	v_add_f32_e32 v243, v157, v243
	v_add_f32_e32 v243, v158, v243
	v_add_f32_e32 v243, v159, v243
	v_add_f32_e32 v196, v196, v243
	v_cvt_pk_bf16_f32 v144, v144, v145
	v_cvt_pk_bf16_f32 v145, v146, v147
	v_cvt_pk_bf16_f32 v146, v148, v149
	v_cvt_pk_bf16_f32 v147, v150, v151
	v_cvt_pk_bf16_f32 v148, v152, v153
	v_cvt_pk_bf16_f32 v149, v154, v155
	v_cvt_pk_bf16_f32 v150, v156, v157
	v_cvt_pk_bf16_f32 v151, v158, v159
	s_waitcnt lgkmcnt(7)
	v_mfma_f32_32x32x16_bf16 v[112:127], v[216:219], v[144:147], v[112:127]
	v_exp_f32_e32 v200, v200
	v_exp_f32_e32 v201, v201
	v_exp_f32_e32 v202, v202
	v_exp_f32_e32 v203, v203
	v_exp_f32_e32 v204, v204
	s_waitcnt lgkmcnt(6)
	v_mfma_f32_32x32x16_bf16 v[80:95], v[224:227], v[144:147], v[80:95]
	v_exp_f32_e32 v205, v205
	v_exp_f32_e32 v206, v206
	v_exp_f32_e32 v207, v207
	v_exp_f32_e32 v208, v208
	v_exp_f32_e32 v209, v209
	s_waitcnt lgkmcnt(5)
	v_mfma_f32_32x32x16_bf16 v[48:63], v[232:235], v[144:147], v[48:63]
	v_exp_f32_e32 v210, v210
	v_exp_f32_e32 v211, v211
	v_exp_f32_e32 v212, v212
	v_exp_f32_e32 v213, v213
	v_exp_f32_e32 v214, v214
	s_waitcnt lgkmcnt(4)
	v_mfma_f32_32x32x16_bf16 v[16:31], v[244:247], v[144:147], v[16:31]
	v_exp_f32_e32 v215, v215
	v_add_f32_e32 v243, v200, v201
	v_add_f32_e32 v243, v202, v243
	v_add_f32_e32 v243, v203, v243
	v_add_f32_e32 v243, v204, v243
	s_waitcnt lgkmcnt(3)
	v_mfma_f32_32x32x16_bf16 v[112:127], v[220:223], v[148:151], v[112:127]
	v_add_f32_e32 v243, v205, v243
	v_add_f32_e32 v243, v206, v243
	v_add_f32_e32 v243, v207, v243
	v_add_f32_e32 v243, v208, v243
	v_add_f32_e32 v243, v209, v243
	s_waitcnt lgkmcnt(2)
	v_mfma_f32_32x32x16_bf16 v[80:95], v[228:231], v[148:151], v[80:95]
	v_add_f32_e32 v243, v210, v243
	v_add_f32_e32 v243, v211, v243
	v_add_f32_e32 v243, v212, v243
	v_add_f32_e32 v243, v213, v243
	v_add_f32_e32 v243, v214, v243
	s_waitcnt lgkmcnt(1)
	v_mfma_f32_32x32x16_bf16 v[48:63], v[236:239], v[148:151], v[48:63]
	v_add_f32_e32 v243, v215, v243
	v_add_f32_e32 v197, v197, v243
	v_cvt_pk_bf16_f32 v200, v200, v201
	v_cvt_pk_bf16_f32 v201, v202, v203
	v_cvt_pk_bf16_f32 v202, v204, v205
	s_waitcnt lgkmcnt(0)
	v_mfma_f32_32x32x16_bf16 v[16:31], v[248:251], v[148:151], v[16:31]
	v_cvt_pk_bf16_f32 v203, v206, v207
	v_cvt_pk_bf16_f32 v204, v208, v209
	v_cvt_pk_bf16_f32 v205, v210, v211
	v_cvt_pk_bf16_f32 v206, v212, v213
	v_cvt_pk_bf16_f32 v207, v214, v215
	s_add_i32 s4, s42, 1
	s_cmp_lt_u32 s4, s98
	s_cbranch_scc1 .LBB0_111
	s_nop 1
	v_mfma_f32_32x32x16_bf16 v[128:143], v[216:219], v[200:203], v[128:143]
	v_mfma_f32_32x32x16_bf16 v[96:111], v[224:227], v[200:203], v[96:111]
	v_mfma_f32_32x32x16_bf16 v[64:79], v[232:235], v[200:203], v[64:79]
	v_mfma_f32_32x32x16_bf16 v[32:47], v[244:247], v[200:203], v[32:47]
	v_mfma_f32_32x32x16_bf16 v[128:143], v[220:223], v[204:207], v[128:143]
	v_mfma_f32_32x32x16_bf16 v[96:111], v[228:231], v[204:207], v[96:111]
	v_mfma_f32_32x32x16_bf16 v[64:79], v[236:239], v[204:207], v[64:79]
	v_mfma_f32_32x32x16_bf16 v[32:47], v[248:251], v[204:207], v[32:47]
	s_branch .LBB0_111
